# P1 table build: second group of partial-sum loads issued together with the first
# baseline (speedup 1.0000x reference)
.LBB0_121:
	s_ashr_i32 s4, s54, 31
	s_lshr_b32 s4, s4, 25
	s_add_i32 s4, s54, s4
	s_ashr_i32 s44, s4, 7
	s_mul_i32 s45, s44, 0x6000
	s_mul_hi_i32 s4, s44, 0x6000
	s_add_u32 s10, s49, s45
	s_addc_u32 s11, s50, s4
	s_add_u32 s14, s10, 0x2000
	s_addc_u32 s15, s11, 0
	s_add_i32 s4, s44, 2
	s_add_i32 s5, s45, 0xc000
	s_mul_hi_i32 s4, s4, 0x6000
	s_add_u32 s16, s49, s5
	s_addc_u32 s17, s50, s4
	s_add_u32 s18, s16, 0x2000
	s_addc_u32 s19, s17, 0
	s_add_i32 s4, s44, 4
	s_add_i32 s5, s45, 0x18000
	s_mul_hi_i32 s8, s4, 0x6000
	s_add_u32 s4, s49, s5
	s_addc_u32 s5, s50, s8
	s_add_u32 s8, s4, 0x2000
	s_addc_u32 s9, s5, 0
	s_add_i32 s20, s44, 6
	s_add_i32 s21, s45, 0x24000
	s_mul_hi_i32 s22, s20, 0x6000
	s_add_u32 s20, s49, s21
	s_addc_u32 s21, s50, s22
	s_add_u32 s22, s20, 0x2000
	s_addc_u32 s23, s21, 0
	s_add_i32 s30, s44, 8
	s_add_i32 s31, s45, 0x30000
	s_mul_hi_i32 s34, s30, 0x6000
	s_add_u32 s30, s49, s31
	s_addc_u32 s31, s50, s34
	s_add_u32 s34, s30, 0x2000
	s_addc_u32 s35, s31, 0
	s_add_i32 s36, s44, 10
	s_add_i32 s37, s45, 0x3c000
	s_mul_hi_i32 s38, s36, 0x6000
	s_add_u32 s36, s49, s37
	s_addc_u32 s37, s50, s38
	s_add_u32 s38, s36, 0x2000
	s_addc_u32 s39, s37, 0
	s_add_i32 s40, s44, 12
	s_add_i32 s41, s45, 0x48000
	s_mul_hi_i32 s42, s40, 0x6000
	s_add_u32 s40, s49, s41
	s_addc_u32 s41, s50, s42
	v_lshl_add_u64 v[2:3], s[10:11], 0, v[14:15]
	v_lshl_add_u64 v[4:5], s[14:15], 0, v[14:15]
	v_lshl_add_u64 v[6:7], s[16:17], 0, v[14:15]
	v_lshl_add_u64 v[38:39], s[18:19], 0, v[14:15]
	v_lshl_add_u64 v[8:9], s[4:5], 0, v[14:15]
	flat_load_dword v71, v[16:17] sc1
	flat_load_dword v72, v[18:19] sc1
	flat_load_dword v73, v[2:3] sc1
	flat_load_dword v74, v[4:5] sc1
	flat_load_dword v75, v[6:7] sc1
	flat_load_dword v76, v[38:39] sc1
	flat_load_dword v77, v[8:9] sc1
	s_add_u32 s42, s40, 0x2000
	s_addc_u32 s43, s41, 0
	s_add_i32 s44, s44, 14
	s_add_i32 s45, s45, 0x54000
	s_mul_hi_i32 s46, s44, 0x6000
	s_add_u32 s44, s49, s45
	v_lshl_add_u64 v[60:61], s[8:9], 0, v[14:15]
	s_addc_u32 s45, s50, s46
	v_lshl_add_u64 v[58:59], s[20:21], 0, v[14:15]
	v_lshl_add_u64 v[56:57], s[22:23], 0, v[14:15]
	v_lshl_add_u64 v[54:55], s[30:31], 0, v[14:15]
	v_lshl_add_u64 v[52:53], s[34:35], 0, v[14:15]
	v_lshl_add_u64 v[50:51], s[36:37], 0, v[14:15]
	v_lshl_add_u64 v[48:49], s[38:39], 0, v[14:15]
	v_lshl_add_u64 v[46:47], s[40:41], 0, v[14:15]
	flat_load_dword v78, v[60:61] sc1
	flat_load_dword v79, v[58:59] sc1
	flat_load_dword v80, v[56:57] sc1
	flat_load_dword v81, v[54:55] sc1
	flat_load_dword v82, v[52:53] sc1
	flat_load_dword v83, v[50:51] sc1
	flat_load_dword v84, v[48:49] sc1
	flat_load_dword v85, v[46:47] sc1
	v_lshl_add_u64 v[44:45], s[42:43], 0, v[14:15]
	s_add_u32 s46, s44, 0x2000
	v_lshl_add_u64 v[42:43], s[44:45], 0, v[14:15]
	flat_load_dword v86, v[44:45] sc1
	flat_load_dword v87, v[42:43] sc1
	s_addc_u32 s47, s45, 0
	v_lshl_add_u64 v[40:41], s[46:47], 0, v[14:15]
	flat_load_dword v88, v[40:41] sc1
	flat_load_dword v89, v[20:21] sc1
	v_lshl_add_u64 v[90:91], s[34:35], 0, v[36:37]
	v_lshl_add_u64 v[92:93], s[36:37], 0, v[36:37]
	v_lshl_add_u64 v[94:95], s[38:39], 0, v[36:37]
	v_lshl_add_u64 v[96:97], s[40:41], 0, v[36:37]
	v_lshl_add_u64 v[98:99], s[42:43], 0, v[36:37]
	v_lshl_add_u64 v[100:101], s[44:45], 0, v[36:37]
	v_lshl_add_u64 v[102:103], s[46:47], 0, v[36:37]
	flat_load_dword v160, v[16:17] offset:2048 sc1
	flat_load_dword v104, v[22:23] sc1
	flat_load_dword v105, v[2:3] offset:2048 sc1
	flat_load_dword v106, v[4:5] offset:2048 sc1
	flat_load_dword v107, v[6:7] offset:2048 sc1
	flat_load_dword v108, v[38:39] offset:2048 sc1
	flat_load_dword v109, v[8:9] offset:2048 sc1
	flat_load_dword v110, v[60:61] offset:2048 sc1
	flat_load_dword v111, v[58:59] offset:2048 sc1
	flat_load_dword v112, v[56:57] offset:2048 sc1
	flat_load_dword v113, v[54:55] offset:2048 sc1
	flat_load_dword v114, v[52:53] offset:2048 sc1
	flat_load_dword v115, v[50:51] offset:2048 sc1
	flat_load_dword v116, v[48:49] offset:2048 sc1
	flat_load_dword v117, v[46:47] offset:2048 sc1
	flat_load_dword v118, v[44:45] offset:2048 sc1
	flat_load_dword v119, v[42:43] offset:2048 sc1
	flat_load_dword v120, v[40:41] offset:2048 sc1
	flat_load_dword v121, v[20:21] offset:2048 sc1
	s_waitcnt vmcnt(0) lgkmcnt(0)
	v_add_f32_e32 v71, v71, v73
	v_add_f32_e32 v72, v72, v74
	v_add_f32_e32 v71, v71, v75
	v_add_f32_e32 v72, v72, v76
	v_add_f32_e32 v71, v71, v77
	v_lshl_add_u64 v[74:75], s[14:15], 0, v[36:37]
	v_lshl_add_u64 v[76:77], s[16:17], 0, v[36:37]
	v_add_f32_e32 v72, v72, v78
	v_add_f32_e32 v71, v71, v79
	v_add_f32_e32 v72, v72, v80
	v_add_f32_e32 v71, v71, v81
	v_add_f32_e32 v72, v72, v82
	v_add_f32_e32 v71, v71, v83
	v_add_f32_e32 v72, v72, v84
	v_add_f32_e32 v71, v71, v85
	v_lshl_add_u64 v[78:79], s[18:19], 0, v[36:37]
	v_lshl_add_u64 v[80:81], s[4:5], 0, v[36:37]
	v_add_f32_e32 v72, v72, v86
	v_add_f32_e32 v71, v71, v87
	ds_write_b32 v68, v71 offset:8192
	v_add_f32_e32 v71, v72, v88
	v_add_f32_e32 v71, 1.0, v71
	v_mul_f32_e32 v71, v71, v89
	ds_write_b32 v68, v71
	v_lshl_add_u64 v[72:73], s[10:11], 0, v[36:37]
	v_lshl_add_u64 v[82:83], s[8:9], 0, v[36:37]
	v_lshl_add_u64 v[84:85], s[20:21], 0, v[36:37]
	v_lshl_add_u64 v[86:87], s[22:23], 0, v[36:37]
	v_lshl_add_u64 v[88:89], s[30:31], 0, v[36:37]
	s_waitcnt vmcnt(0) lgkmcnt(0)
	v_add_f32_e32 v71, v160, v105
	v_add_f32_e32 v104, v104, v106
	v_add_f32_e32 v71, v71, v107
	v_add_f32_e32 v104, v104, v108
	v_add_f32_e32 v71, v71, v109
	v_add_f32_e32 v104, v104, v110
	v_add_f32_e32 v71, v71, v111
	v_add_f32_e32 v104, v104, v112
	v_add_f32_e32 v71, v71, v113
	v_add_f32_e32 v104, v104, v114
	v_add_f32_e32 v71, v71, v115
	v_add_f32_e32 v104, v104, v116
	v_add_f32_e32 v71, v71, v117
	v_add_f32_e32 v104, v104, v118
	v_add_f32_e32 v71, v71, v119
	v_add_f32_e32 v104, v104, v120
	v_add_f32_e32 v104, 1.0, v104
	ds_write_b32 v68, v71 offset:10240
	v_mul_f32_e32 v71, v104, v121
	ds_write_b32 v68, v71 offset:2048
	flat_load_dword v71, v[72:73] sc1
	s_nop 0
	flat_load_dword v72, v[74:75] sc1
	flat_load_dword v73, v[24:25] sc1
	flat_load_dword v104, v[26:27] sc1
	flat_load_dword v105, v[76:77] sc1
	flat_load_dword v106, v[78:79] sc1
	flat_load_dword v107, v[80:81] sc1
	flat_load_dword v108, v[82:83] sc1
	flat_load_dword v109, v[84:85] sc1
	flat_load_dword v110, v[86:87] sc1
	flat_load_dword v111, v[88:89] sc1
	flat_load_dword v112, v[90:91] sc1
	flat_load_dword v113, v[92:93] sc1
	flat_load_dword v114, v[94:95] sc1
	flat_load_dword v115, v[96:97] sc1
	flat_load_dword v116, v[98:99] sc1
	flat_load_dword v74, v[100:101] sc1
	flat_load_dword v75, v[102:103] sc1
	flat_load_dword v76, v[28:29] sc1
	s_waitcnt vmcnt(0) lgkmcnt(0)
	v_add_f32_e32 v71, v73, v71
	v_add_f32_e32 v72, v104, v72
	v_add_f32_e32 v71, v71, v105
	v_add_f32_e32 v72, v72, v106
	v_add_f32_e32 v71, v71, v107
	v_add_f32_e32 v72, v72, v108
	v_add_f32_e32 v71, v71, v109
	v_add_f32_e32 v72, v72, v110
	v_add_f32_e32 v71, v71, v111
	v_add_f32_e32 v72, v72, v112
	v_add_f32_e32 v71, v71, v113
	v_add_f32_e32 v72, v72, v114
	v_add_f32_e32 v71, v71, v115
	v_add_f32_e32 v72, v72, v116
	v_add_f32_e32 v71, v71, v74
	v_add_f32_e32 v72, v72, v75
	v_add_f32_e32 v72, 1.0, v72
	v_mul_f32_e32 v72, v72, v76
	ds_write_b32 v68, v72 offset:4096
	ds_write_b32 v68, v71 offset:12288
	s_and_saveexec_b64 s[4:5], s[6:7]
	s_cbranch_execz .LBB0_123
	v_add_co_u32_e32 v2, vcc, 0x1000, v2
	s_nop 1
	v_addc_co_u32_e32 v3, vcc, 0, v3, vcc
	v_add_co_u32_e32 v4, vcc, 0x1000, v4
	s_nop 1
	v_addc_co_u32_e32 v5, vcc, 0, v5, vcc
	v_add_co_u32_e32 v6, vcc, 0x1000, v6
	s_nop 1
	v_addc_co_u32_e32 v7, vcc, 0, v7, vcc
	v_add_co_u32_e32 v38, vcc, 0x1000, v38
	s_nop 1
	v_addc_co_u32_e32 v39, vcc, 0, v39, vcc
	v_add_co_u32_e32 v8, vcc, 0x1000, v8
	s_nop 1
	v_addc_co_u32_e32 v9, vcc, 0, v9, vcc
	flat_load_dword v71, v[30:31] sc1
	flat_load_dword v72, v[32:33] sc1
	flat_load_dword v73, v[2:3] offset:2048 sc1
	flat_load_dword v74, v[4:5] offset:2048 sc1
	flat_load_dword v75, v[6:7] offset:2048 sc1
	flat_load_dword v76, v[38:39] offset:2048 sc1
	flat_load_dword v77, v[8:9] offset:2048 sc1
	v_add_co_u32_e32 v2, vcc, 0x1000, v60
	s_nop 1
	v_addc_co_u32_e32 v3, vcc, 0, v61, vcc
	v_add_co_u32_e32 v4, vcc, 0x1000, v58
	s_nop 1
	v_addc_co_u32_e32 v5, vcc, 0, v59, vcc
	v_add_co_u32_e32 v6, vcc, 0x1000, v56
	s_nop 1
	v_addc_co_u32_e32 v7, vcc, 0, v57, vcc
	v_add_co_u32_e32 v8, vcc, 0x1000, v54
	s_nop 1
	v_addc_co_u32_e32 v9, vcc, 0, v55, vcc
	v_add_co_u32_e32 v38, vcc, 0x1000, v52
	s_nop 1
	v_addc_co_u32_e32 v39, vcc, 0, v53, vcc
	v_add_co_u32_e32 v50, vcc, 0x1000, v50
	s_nop 1
	v_addc_co_u32_e32 v51, vcc, 0, v51, vcc
	v_add_co_u32_e32 v48, vcc, 0x1000, v48
	s_nop 1
	v_addc_co_u32_e32 v49, vcc, 0, v49, vcc
	v_add_co_u32_e32 v46, vcc, 0x1000, v46
	s_nop 1
	v_addc_co_u32_e32 v47, vcc, 0, v47, vcc
	flat_load_dword v52, v[2:3] offset:2048 sc1
	flat_load_dword v53, v[4:5] offset:2048 sc1
	flat_load_dword v54, v[6:7] offset:2048 sc1
	flat_load_dword v55, v[8:9] offset:2048 sc1
	flat_load_dword v56, v[38:39] offset:2048 sc1
	flat_load_dword v57, v[50:51] offset:2048 sc1
	flat_load_dword v58, v[48:49] offset:2048 sc1
	flat_load_dword v59, v[46:47] offset:2048 sc1
	v_add_co_u32_e32 v2, vcc, 0x1000, v44
	s_nop 1
	v_addc_co_u32_e32 v3, vcc, 0, v45, vcc
	v_add_co_u32_e32 v4, vcc, 0x1000, v42
	s_nop 1
	v_addc_co_u32_e32 v5, vcc, 0, v43, vcc
	v_add_co_u32_e32 v6, vcc, 0x1000, v40
	s_nop 1
	v_addc_co_u32_e32 v7, vcc, 0, v41, vcc
	flat_load_dword v8, v[2:3] offset:2048 sc1
	flat_load_dword v9, v[4:5] offset:2048 sc1
	flat_load_dword v38, v[6:7] offset:2048 sc1
	flat_load_dword v39, v[34:35] sc1
	s_waitcnt vmcnt(0) lgkmcnt(0)
	v_add_f32_e32 v2, v71, v73
	v_add_f32_e32 v3, v72, v74
	v_add_f32_e32 v2, v2, v75
	v_add_f32_e32 v3, v3, v76
	v_add_f32_e32 v2, v2, v77
	v_add_f32_e32 v3, v3, v52
	v_add_f32_e32 v2, v2, v53
	v_add_f32_e32 v3, v3, v54
	v_add_f32_e32 v2, v2, v55
	v_add_f32_e32 v3, v3, v56
	v_add_f32_e32 v2, v2, v57
	v_add_f32_e32 v3, v3, v58
	v_add_f32_e32 v2, v2, v59
	v_add_f32_e32 v3, v3, v8
	v_add_f32_e32 v2, v2, v9
	v_add_f32_e32 v3, v3, v38
	v_add_f32_e32 v3, 1.0, v3
	v_mul_f32_e32 v3, v3, v39
	ds_write2st64_b32 v68, v3, v2 offset0:24 offset1:56
